# attn fixed-ref kt loops incl. band-masked chunks, MFMA/VALU interleaved
# speedup vs baseline: 1.0125x; 1.0042x over previous
.LBB0_431:
	s_cmp_eq_u32 s73, 2
	s_cselect_b64 s[58:59], -1, 0
	s_cmp_lg_u32 s73, 2
	v_cvt_pk_bf16_f32 v96, v91, v95
	v_cvt_pk_bf16_f32 v97, v103, v107
	s_cselect_b64 s[62:63], -1, 0
	s_cmp_eq_u32 s73, 4
	v_cvt_pk_bf16_f32 v98, v105, v101
	v_cvt_pk_bf16_f32 v99, v93, v89
	ds_write_b128 v233, v[96:99]
	v_cvt_pk_bf16_f32 v94, v90, v94
	v_cvt_pk_bf16_f32 v95, v102, v106
	v_cvt_pk_bf16_f32 v96, v104, v100
	v_cvt_pk_bf16_f32 v97, v92, v88
	s_mov_b32 s8, 0
	s_cselect_b64 s[64:65], -1, 0
	v_mov_b32_e32 v203, v232
	v_mov_b32_e32 v205, v231
	s_mov_b32 s87, 0
	ds_write_b128 v233, v[94:97] offset:4096
	ds_write_b128 v234, v[84:87] offset:16384
	ds_write_b128 v234, v[80:83] offset:16400
	s_waitcnt lgkmcnt(0)
	s_barrier
	s_cmp_eq_u64 s[2:3], 0
	s_cbranch_scc1 .Lfx_entry

.Lfx_entry:
	v_mov_b32_e32 v237, v112
	v_mov_b32_e32 v236, v113
	s_movk_i32 s66, 0x80
	s_and_b64 vcc, exec, s[58:59]
	s_cbranch_vccnz .Lfx_c2
	s_and_b64 vcc, exec, s[64:65]
	s_cbranch_vccnz .Lfx_c4
	ds_read_b128 v[176:179], v203
	ds_read_b128 v[180:183], v203 offset:4096
	ds_read_b128 v[184:187], v203 offset:8192
	ds_read_b128 v[188:191], v203 offset:12288
.Lfx_loop_n:
	ds_read_b64_tr_b16 v[96:97], v205 offset:16384
	ds_read_b64_tr_b16 v[98:99], v205 offset:16896
	ds_read_b64_tr_b16 v[100:101], v205 offset:17408
	ds_read_b64_tr_b16 v[102:103], v205 offset:17920
	ds_read_b64_tr_b16 v[104:105], v205 offset:24576
	ds_read_b64_tr_b16 v[106:107], v205 offset:25088
	ds_read_b64_tr_b16 v[108:109], v205 offset:25600
	ds_read_b64_tr_b16 v[110:111], v205 offset:26112
	s_waitcnt lgkmcnt(8)
	v_mfma_f32_32x32x16_bf16 v[80:95], v[176:179], v[128:131], v[48:63]
	v_mfma_f32_32x32x16_bf16 v[80:95], v[180:183], v[132:135], v[80:95]
	v_mfma_f32_32x32x16_bf16 v[80:95], v[184:187], v[136:139], v[80:95]
	v_mfma_f32_32x32x16_bf16 v[80:95], v[188:191], v[140:143], v[80:95]
	v_add_u32_e32 v203, 0x200, v203
	s_add_i32 s8, s8, 32
	s_nop 9
	v_mfma_f32_32x32x16_bf16 v[112:127], v[176:179], v[144:147], v[48:63]
	v_exp_f32_e32 v80, v80
	v_exp_f32_e32 v81, v81
	v_exp_f32_e32 v82, v82
	v_add_f32_e32 v240, v80, v81
	v_exp_f32_e32 v83, v83
	v_add_f32_e32 v240, v240, v82
	v_exp_f32_e32 v84, v84
	v_add_f32_e32 v240, v240, v83
	v_mfma_f32_32x32x16_bf16 v[112:127], v[180:183], v[148:151], v[112:127]
	v_exp_f32_e32 v85, v85
	v_exp_f32_e32 v86, v86
	v_add_f32_e32 v241, v84, v85
	v_exp_f32_e32 v87, v87
	v_add_f32_e32 v241, v241, v86
	v_exp_f32_e32 v88, v88
	v_add_f32_e32 v241, v241, v87
	v_exp_f32_e32 v89, v89
	v_mfma_f32_32x32x16_bf16 v[112:127], v[184:187], v[152:155], v[112:127]
	v_exp_f32_e32 v90, v90
	v_add_f32_e32 v242, v88, v89
	v_exp_f32_e32 v91, v91
	v_add_f32_e32 v242, v242, v90
	v_exp_f32_e32 v92, v92
	v_add_f32_e32 v242, v242, v91
	v_exp_f32_e32 v93, v93
	v_exp_f32_e32 v94, v94
	v_mfma_f32_32x32x16_bf16 v[112:127], v[188:191], v[156:159], v[112:127]
	v_add_f32_e32 v243, v92, v93
	v_exp_f32_e32 v95, v95
	v_add_f32_e32 v243, v243, v94
	v_add_f32_e32 v240, v240, v241
	v_add_f32_e32 v243, v243, v95
	v_add_f32_e32 v242, v242, v243
	v_add_f32_e32 v240, v240, v242
	v_add_f32_e32 v237, v237, v240
	v_cvt_pk_bf16_f32 v80, v80, v81
	v_cvt_pk_bf16_f32 v81, v82, v83
	v_cvt_pk_bf16_f32 v82, v84, v85
	v_cvt_pk_bf16_f32 v83, v86, v87
	v_cvt_pk_bf16_f32 v84, v88, v89
	v_cvt_pk_bf16_f32 v85, v90, v91
	v_cvt_pk_bf16_f32 v86, v92, v93
	v_cvt_pk_bf16_f32 v87, v94, v95
	s_waitcnt lgkmcnt(0)
	s_cmp_eq_u32 s8, s66
	s_cbranch_scc1 .Lfx_nopref_n
	ds_read_b128 v[176:179], v203
	ds_read_b128 v[180:183], v203 offset:4096
	ds_read_b128 v[184:187], v203 offset:8192
	ds_read_b128 v[188:191], v203 offset:12288
.Lfx_nopref_n:
	v_mfma_f32_32x32x16_bf16 v[64:79], v[96:99], v[80:83], v[64:79]
	v_exp_f32_e32 v112, v112
	v_exp_f32_e32 v113, v113
	v_exp_f32_e32 v114, v114
	v_add_f32_e32 v240, v112, v113
	v_exp_f32_e32 v115, v115
	v_add_f32_e32 v240, v240, v114
	v_exp_f32_e32 v116, v116
	v_add_f32_e32 v240, v240, v115
	v_mfma_f32_32x32x16_bf16 v[32:47], v[104:107], v[80:83], v[32:47]
	v_exp_f32_e32 v117, v117
	v_exp_f32_e32 v118, v118
	v_add_f32_e32 v241, v116, v117
	v_exp_f32_e32 v119, v119
	v_add_f32_e32 v241, v241, v118
	v_exp_f32_e32 v120, v120
	v_add_f32_e32 v241, v241, v119
	v_exp_f32_e32 v121, v121
	v_mfma_f32_32x32x16_bf16 v[64:79], v[100:103], v[84:87], v[64:79]
	v_exp_f32_e32 v122, v122
	v_add_f32_e32 v242, v120, v121
	v_exp_f32_e32 v123, v123
	v_add_f32_e32 v242, v242, v122
	v_exp_f32_e32 v124, v124
	v_add_f32_e32 v242, v242, v123
	v_exp_f32_e32 v125, v125
	v_exp_f32_e32 v126, v126
	v_mfma_f32_32x32x16_bf16 v[32:47], v[108:111], v[84:87], v[32:47]
	v_add_f32_e32 v243, v124, v125
	v_exp_f32_e32 v127, v127
	v_add_f32_e32 v243, v243, v126
	v_add_f32_e32 v240, v240, v241
	v_add_f32_e32 v243, v243, v127
	v_add_f32_e32 v242, v242, v243
	v_add_f32_e32 v240, v240, v242
	v_add_f32_e32 v227, v227, v240
	v_cvt_pk_bf16_f32 v112, v112, v113
	v_cvt_pk_bf16_f32 v113, v114, v115
	v_cvt_pk_bf16_f32 v114, v116, v117
	v_cvt_pk_bf16_f32 v115, v118, v119
	v_cvt_pk_bf16_f32 v116, v120, v121
	v_cvt_pk_bf16_f32 v117, v122, v123
	v_cvt_pk_bf16_f32 v118, v124, v125
	v_cvt_pk_bf16_f32 v119, v126, v127
	v_mfma_f32_32x32x16_bf16 v[16:31], v[96:99], v[112:115], v[16:31]
	v_mfma_f32_32x32x16_bf16 v[0:15], v[104:107], v[112:115], v[0:15]
	v_mfma_f32_32x32x16_bf16 v[16:31], v[100:103], v[116:119], v[16:31]
	v_mfma_f32_32x32x16_bf16 v[0:15], v[108:111], v[116:119], v[0:15]
	v_add_u32_e32 v205, 0x800, v205
	s_cmp_lg_u32 s8, s66
	s_cbranch_scc1 .Lfx_loop_n
	s_branch .Lfx_exit
.Lfx_c2:
	s_lshl_b32 s8, s85, 5
	s_lshl_b32 s67, s85, 9
	v_add_u32_e32 v203, s67, v203
	s_lshl_b32 s67, s85, 11
	v_add_u32_e32 v205, s67, v205
	ds_read_b128 v[176:179], v203
	ds_read_b128 v[180:183], v203 offset:4096
	ds_read_b128 v[184:187], v203 offset:8192
	ds_read_b128 v[188:191], v203 offset:12288
.Lfx_loop_c2:
	ds_read_b64_tr_b16 v[96:97], v205 offset:16384
	ds_read_b64_tr_b16 v[98:99], v205 offset:16896
	ds_read_b64_tr_b16 v[100:101], v205 offset:17408
	ds_read_b64_tr_b16 v[102:103], v205 offset:17920
	ds_read_b64_tr_b16 v[104:105], v205 offset:24576
	ds_read_b64_tr_b16 v[106:107], v205 offset:25088
	ds_read_b64_tr_b16 v[108:109], v205 offset:25600
	ds_read_b64_tr_b16 v[110:111], v205 offset:26112
	s_waitcnt lgkmcnt(8)
	v_mfma_f32_32x32x16_bf16 v[80:95], v[176:179], v[128:131], v[48:63]
	v_mfma_f32_32x32x16_bf16 v[80:95], v[180:183], v[132:135], v[80:95]
	v_mfma_f32_32x32x16_bf16 v[80:95], v[184:187], v[136:139], v[80:95]
	v_mfma_f32_32x32x16_bf16 v[80:95], v[188:191], v[140:143], v[80:95]
	v_add_u32_e32 v238, s8, v228
	v_add_u32_e32 v203, 0x200, v203
	s_add_i32 s8, s8, 32
	v_sub_u32_e32 v238, v229, v238
	v_add_u32_e32 v239, 32, v238
	s_nop 6
	v_mfma_f32_32x32x16_bf16 v[112:127], v[176:179], v[144:147], v[48:63]
	v_cmp_ge_i32_e32 vcc, 0, v238
	v_cmp_ge_i32_e64 s[98:99], 1, v238
	v_cmp_ge_i32_e64 s[100:101], 2, v238
	v_cndmask_b32_e32 v80, v220, v80, vcc
	v_cmp_ge_i32_e32 vcc, 3, v238
	v_exp_f32_e32 v80, v80
	v_cndmask_b32_e64 v81, v220, v81, s[98:99]
	v_cmp_ge_i32_e64 s[98:99], 8, v238
	v_exp_f32_e32 v81, v81
	v_cndmask_b32_e64 v82, v220, v82, s[100:101]
	v_cmp_ge_i32_e64 s[100:101], 9, v238
	v_exp_f32_e32 v82, v82
	v_add_f32_e32 v240, v80, v81
	v_cndmask_b32_e32 v83, v220, v83, vcc
	v_cmp_ge_i32_e32 vcc, 10, v238
	v_exp_f32_e32 v83, v83
	v_mfma_f32_32x32x16_bf16 v[112:127], v[180:183], v[148:151], v[112:127]
	v_add_f32_e32 v240, v240, v82
	v_cndmask_b32_e64 v84, v220, v84, s[98:99]
	v_cmp_ge_i32_e64 s[98:99], 11, v238
	v_exp_f32_e32 v84, v84
	v_add_f32_e32 v240, v240, v83
	v_cndmask_b32_e64 v85, v220, v85, s[100:101]
	v_cmp_ge_i32_e64 s[100:101], 16, v238
	v_exp_f32_e32 v85, v85
	v_cndmask_b32_e32 v86, v220, v86, vcc
	v_cmp_ge_i32_e32 vcc, 17, v238
	v_exp_f32_e32 v86, v86
	v_add_f32_e32 v241, v84, v85
	v_cndmask_b32_e64 v87, v220, v87, s[98:99]
	v_cmp_ge_i32_e64 s[98:99], 18, v238
	v_exp_f32_e32 v87, v87
	v_add_f32_e32 v241, v241, v86
	v_mfma_f32_32x32x16_bf16 v[112:127], v[184:187], v[152:155], v[112:127]
	v_cndmask_b32_e64 v88, v220, v88, s[100:101]
	v_cmp_ge_i32_e64 s[100:101], 19, v238
	v_exp_f32_e32 v88, v88
	v_add_f32_e32 v241, v241, v87
	v_cndmask_b32_e32 v89, v220, v89, vcc
	v_cmp_ge_i32_e32 vcc, 24, v238
	v_exp_f32_e32 v89, v89
	v_cndmask_b32_e64 v90, v220, v90, s[98:99]
	v_cmp_ge_i32_e64 s[98:99], 25, v238
	v_exp_f32_e32 v90, v90
	v_add_f32_e32 v242, v88, v89
	v_cndmask_b32_e64 v91, v220, v91, s[100:101]
	v_cmp_ge_i32_e64 s[100:101], 26, v238
	v_exp_f32_e32 v91, v91
	v_add_f32_e32 v242, v242, v90
	v_cndmask_b32_e32 v92, v220, v92, vcc
	v_mfma_f32_32x32x16_bf16 v[112:127], v[188:191], v[156:159], v[112:127]
	v_cmp_ge_i32_e32 vcc, 27, v238
	v_exp_f32_e32 v92, v92
	v_add_f32_e32 v242, v242, v91
	v_cndmask_b32_e64 v93, v220, v93, s[98:99]
	v_exp_f32_e32 v93, v93
	v_cndmask_b32_e64 v94, v220, v94, s[100:101]
	v_exp_f32_e32 v94, v94
	v_add_f32_e32 v243, v92, v93
	v_cndmask_b32_e32 v95, v220, v95, vcc
	v_exp_f32_e32 v95, v95
	v_add_f32_e32 v243, v243, v94
	v_add_f32_e32 v240, v240, v241
	v_add_f32_e32 v243, v243, v95
	v_add_f32_e32 v242, v242, v243
	v_add_f32_e32 v240, v240, v242
	v_add_f32_e32 v237, v237, v240
	v_cvt_pk_bf16_f32 v80, v80, v81
	v_cvt_pk_bf16_f32 v81, v82, v83
	v_cvt_pk_bf16_f32 v82, v84, v85
	v_cvt_pk_bf16_f32 v83, v86, v87
	v_cvt_pk_bf16_f32 v84, v88, v89
	v_cvt_pk_bf16_f32 v85, v90, v91
	v_cvt_pk_bf16_f32 v86, v92, v93
	v_cvt_pk_bf16_f32 v87, v94, v95
	s_waitcnt lgkmcnt(0)
	s_cmp_eq_u32 s8, s66
	s_cbranch_scc1 .Lfx_nopref_c2
	ds_read_b128 v[176:179], v203
	ds_read_b128 v[180:183], v203 offset:4096
	ds_read_b128 v[184:187], v203 offset:8192
	ds_read_b128 v[188:191], v203 offset:12288
.Lfx_nopref_c2:
	v_mfma_f32_32x32x16_bf16 v[64:79], v[96:99], v[80:83], v[64:79]
	v_cmp_ge_i32_e32 vcc, 0, v239
	v_cmp_ge_i32_e64 s[98:99], 1, v239
	v_cmp_ge_i32_e64 s[100:101], 2, v239
	v_cndmask_b32_e32 v112, v220, v112, vcc
	v_cmp_ge_i32_e32 vcc, 3, v239
	v_exp_f32_e32 v112, v112
	v_cndmask_b32_e64 v113, v220, v113, s[98:99]
	v_cmp_ge_i32_e64 s[98:99], 8, v239
	v_exp_f32_e32 v113, v113
	v_cndmask_b32_e64 v114, v220, v114, s[100:101]
	v_cmp_ge_i32_e64 s[100:101], 9, v239
	v_exp_f32_e32 v114, v114
	v_add_f32_e32 v240, v112, v113
	v_cndmask_b32_e32 v115, v220, v115, vcc
	v_cmp_ge_i32_e32 vcc, 10, v239
	v_exp_f32_e32 v115, v115
	v_mfma_f32_32x32x16_bf16 v[32:47], v[104:107], v[80:83], v[32:47]
	v_add_f32_e32 v240, v240, v114
	v_cndmask_b32_e64 v116, v220, v116, s[98:99]
	v_cmp_ge_i32_e64 s[98:99], 11, v239
	v_exp_f32_e32 v116, v116
	v_add_f32_e32 v240, v240, v115
	v_cndmask_b32_e64 v117, v220, v117, s[100:101]
	v_cmp_ge_i32_e64 s[100:101], 16, v239
	v_exp_f32_e32 v117, v117
	v_cndmask_b32_e32 v118, v220, v118, vcc
	v_cmp_ge_i32_e32 vcc, 17, v239
	v_exp_f32_e32 v118, v118
	v_add_f32_e32 v241, v116, v117
	v_cndmask_b32_e64 v119, v220, v119, s[98:99]
	v_cmp_ge_i32_e64 s[98:99], 18, v239
	v_exp_f32_e32 v119, v119
	v_add_f32_e32 v241, v241, v118
	v_mfma_f32_32x32x16_bf16 v[64:79], v[100:103], v[84:87], v[64:79]
	v_cndmask_b32_e64 v120, v220, v120, s[100:101]
	v_cmp_ge_i32_e64 s[100:101], 19, v239
	v_exp_f32_e32 v120, v120
	v_add_f32_e32 v241, v241, v119
	v_cndmask_b32_e32 v121, v220, v121, vcc
	v_cmp_ge_i32_e32 vcc, 24, v239
	v_exp_f32_e32 v121, v121
	v_cndmask_b32_e64 v122, v220, v122, s[98:99]
	v_cmp_ge_i32_e64 s[98:99], 25, v239
	v_exp_f32_e32 v122, v122
	v_add_f32_e32 v242, v120, v121
	v_cndmask_b32_e64 v123, v220, v123, s[100:101]
	v_cmp_ge_i32_e64 s[100:101], 26, v239
	v_exp_f32_e32 v123, v123
	v_add_f32_e32 v242, v242, v122
	v_cndmask_b32_e32 v124, v220, v124, vcc
	v_mfma_f32_32x32x16_bf16 v[32:47], v[108:111], v[84:87], v[32:47]
	v_cmp_ge_i32_e32 vcc, 27, v239
	v_exp_f32_e32 v124, v124
	v_add_f32_e32 v242, v242, v123
	v_cndmask_b32_e64 v125, v220, v125, s[98:99]
	v_exp_f32_e32 v125, v125
	v_cndmask_b32_e64 v126, v220, v126, s[100:101]
	v_exp_f32_e32 v126, v126
	v_add_f32_e32 v243, v124, v125
	v_cndmask_b32_e32 v127, v220, v127, vcc
	v_exp_f32_e32 v127, v127
	v_add_f32_e32 v243, v243, v126
	v_add_f32_e32 v240, v240, v241
	v_add_f32_e32 v243, v243, v127
	v_add_f32_e32 v242, v242, v243
	v_add_f32_e32 v240, v240, v242
	v_add_f32_e32 v227, v227, v240
	v_cvt_pk_bf16_f32 v112, v112, v113
	v_cvt_pk_bf16_f32 v113, v114, v115
	v_cvt_pk_bf16_f32 v114, v116, v117
	v_cvt_pk_bf16_f32 v115, v118, v119
	v_cvt_pk_bf16_f32 v116, v120, v121
	v_cvt_pk_bf16_f32 v117, v122, v123
	v_cvt_pk_bf16_f32 v118, v124, v125
	v_cvt_pk_bf16_f32 v119, v126, v127
	v_mfma_f32_32x32x16_bf16 v[16:31], v[96:99], v[112:115], v[16:31]
	v_mfma_f32_32x32x16_bf16 v[0:15], v[104:107], v[112:115], v[0:15]
	v_mfma_f32_32x32x16_bf16 v[16:31], v[100:103], v[116:119], v[16:31]
	v_mfma_f32_32x32x16_bf16 v[0:15], v[108:111], v[116:119], v[0:15]
	v_add_u32_e32 v205, 0x800, v205
	s_cmp_lg_u32 s8, s66
	s_cbranch_scc1 .Lfx_loop_c2
	s_branch .Lfx_exit
.Lfx_c4:
	s_lshl_b32 s66, s86, 5
	s_add_i32 s66, s66, 32
	ds_read_b128 v[176:179], v203
	ds_read_b128 v[180:183], v203 offset:4096
	ds_read_b128 v[184:187], v203 offset:8192
	ds_read_b128 v[188:191], v203 offset:12288
.Lfx_loop_c4:
	ds_read_b64_tr_b16 v[96:97], v205 offset:16384
	ds_read_b64_tr_b16 v[98:99], v205 offset:16896
	ds_read_b64_tr_b16 v[100:101], v205 offset:17408
	ds_read_b64_tr_b16 v[102:103], v205 offset:17920
	ds_read_b64_tr_b16 v[104:105], v205 offset:24576
	ds_read_b64_tr_b16 v[106:107], v205 offset:25088
	ds_read_b64_tr_b16 v[108:109], v205 offset:25600
	ds_read_b64_tr_b16 v[110:111], v205 offset:26112
	s_waitcnt lgkmcnt(8)
	v_mfma_f32_32x32x16_bf16 v[80:95], v[176:179], v[128:131], v[48:63]
	v_mfma_f32_32x32x16_bf16 v[80:95], v[180:183], v[132:135], v[80:95]
	v_mfma_f32_32x32x16_bf16 v[80:95], v[184:187], v[136:139], v[80:95]
	v_mfma_f32_32x32x16_bf16 v[80:95], v[188:191], v[140:143], v[80:95]
	v_add_u32_e32 v238, s8, v228
	v_add_u32_e32 v203, 0x200, v203
	s_add_i32 s8, s8, 32
	v_sub_u32_e32 v238, v229, v238
	v_add_u32_e32 v239, 32, v238
	s_nop 6
	v_mfma_f32_32x32x16_bf16 v[112:127], v[176:179], v[144:147], v[48:63]
	v_cmp_le_i32_e32 vcc, 0, v238
	v_cmp_le_i32_e64 s[98:99], 1, v238
	v_cmp_le_i32_e64 s[100:101], 2, v238
	v_cndmask_b32_e32 v80, v220, v80, vcc
	v_cmp_le_i32_e32 vcc, 3, v238
	v_exp_f32_e32 v80, v80
	v_cndmask_b32_e64 v81, v220, v81, s[98:99]
	v_cmp_le_i32_e64 s[98:99], 8, v238
	v_exp_f32_e32 v81, v81
	v_cndmask_b32_e64 v82, v220, v82, s[100:101]
	v_cmp_le_i32_e64 s[100:101], 9, v238
	v_exp_f32_e32 v82, v82
	v_add_f32_e32 v240, v80, v81
	v_cndmask_b32_e32 v83, v220, v83, vcc
	v_cmp_le_i32_e32 vcc, 10, v238
	v_exp_f32_e32 v83, v83
	v_mfma_f32_32x32x16_bf16 v[112:127], v[180:183], v[148:151], v[112:127]
	v_add_f32_e32 v240, v240, v82
	v_cndmask_b32_e64 v84, v220, v84, s[98:99]
	v_cmp_le_i32_e64 s[98:99], 11, v238
	v_exp_f32_e32 v84, v84
	v_add_f32_e32 v240, v240, v83
	v_cndmask_b32_e64 v85, v220, v85, s[100:101]
	v_cmp_le_i32_e64 s[100:101], 16, v238
	v_exp_f32_e32 v85, v85
	v_cndmask_b32_e32 v86, v220, v86, vcc
	v_cmp_le_i32_e32 vcc, 17, v238
	v_exp_f32_e32 v86, v86
	v_add_f32_e32 v241, v84, v85
	v_cndmask_b32_e64 v87, v220, v87, s[98:99]
	v_cmp_le_i32_e64 s[98:99], 18, v238
	v_exp_f32_e32 v87, v87
	v_add_f32_e32 v241, v241, v86
	v_mfma_f32_32x32x16_bf16 v[112:127], v[184:187], v[152:155], v[112:127]
	v_cndmask_b32_e64 v88, v220, v88, s[100:101]
	v_cmp_le_i32_e64 s[100:101], 19, v238
	v_exp_f32_e32 v88, v88
	v_add_f32_e32 v241, v241, v87
	v_cndmask_b32_e32 v89, v220, v89, vcc
	v_cmp_le_i32_e32 vcc, 24, v238
	v_exp_f32_e32 v89, v89
	v_cndmask_b32_e64 v90, v220, v90, s[98:99]
	v_cmp_le_i32_e64 s[98:99], 25, v238
	v_exp_f32_e32 v90, v90
	v_add_f32_e32 v242, v88, v89
	v_cndmask_b32_e64 v91, v220, v91, s[100:101]
	v_cmp_le_i32_e64 s[100:101], 26, v238
	v_exp_f32_e32 v91, v91
	v_add_f32_e32 v242, v242, v90
	v_cndmask_b32_e32 v92, v220, v92, vcc
	v_mfma_f32_32x32x16_bf16 v[112:127], v[188:191], v[156:159], v[112:127]
	v_cmp_le_i32_e32 vcc, 27, v238
	v_exp_f32_e32 v92, v92
	v_add_f32_e32 v242, v242, v91
	v_cndmask_b32_e64 v93, v220, v93, s[98:99]
	v_exp_f32_e32 v93, v93
	v_cndmask_b32_e64 v94, v220, v94, s[100:101]
	v_exp_f32_e32 v94, v94
	v_add_f32_e32 v243, v92, v93
	v_cndmask_b32_e32 v95, v220, v95, vcc
	v_exp_f32_e32 v95, v95
	v_add_f32_e32 v243, v243, v94
	v_add_f32_e32 v240, v240, v241
	v_add_f32_e32 v243, v243, v95
	v_add_f32_e32 v242, v242, v243
	v_add_f32_e32 v240, v240, v242
	v_add_f32_e32 v237, v237, v240
	v_cvt_pk_bf16_f32 v80, v80, v81
	v_cvt_pk_bf16_f32 v81, v82, v83
	v_cvt_pk_bf16_f32 v82, v84, v85
	v_cvt_pk_bf16_f32 v83, v86, v87
	v_cvt_pk_bf16_f32 v84, v88, v89
	v_cvt_pk_bf16_f32 v85, v90, v91
	v_cvt_pk_bf16_f32 v86, v92, v93
	v_cvt_pk_bf16_f32 v87, v94, v95
	s_waitcnt lgkmcnt(0)
	s_cmp_eq_u32 s8, s66
	s_cbranch_scc1 .Lfx_nopref_c4
	ds_read_b128 v[176:179], v203
	ds_read_b128 v[180:183], v203 offset:4096
	ds_read_b128 v[184:187], v203 offset:8192
	ds_read_b128 v[188:191], v203 offset:12288
.Lfx_nopref_c4:
	v_mfma_f32_32x32x16_bf16 v[64:79], v[96:99], v[80:83], v[64:79]
	v_cmp_le_i32_e32 vcc, 0, v239
	v_cmp_le_i32_e64 s[98:99], 1, v239
	v_cmp_le_i32_e64 s[100:101], 2, v239
	v_cndmask_b32_e32 v112, v220, v112, vcc
	v_cmp_le_i32_e32 vcc, 3, v239
	v_exp_f32_e32 v112, v112
	v_cndmask_b32_e64 v113, v220, v113, s[98:99]
	v_cmp_le_i32_e64 s[98:99], 8, v239
	v_exp_f32_e32 v113, v113
	v_cndmask_b32_e64 v114, v220, v114, s[100:101]
	v_cmp_le_i32_e64 s[100:101], 9, v239
	v_exp_f32_e32 v114, v114
	v_add_f32_e32 v240, v112, v113
	v_cndmask_b32_e32 v115, v220, v115, vcc
	v_cmp_le_i32_e32 vcc, 10, v239
	v_exp_f32_e32 v115, v115
	v_mfma_f32_32x32x16_bf16 v[32:47], v[104:107], v[80:83], v[32:47]
	v_add_f32_e32 v240, v240, v114
	v_cndmask_b32_e64 v116, v220, v116, s[98:99]
	v_cmp_le_i32_e64 s[98:99], 11, v239
	v_exp_f32_e32 v116, v116
	v_add_f32_e32 v240, v240, v115
	v_cndmask_b32_e64 v117, v220, v117, s[100:101]
	v_cmp_le_i32_e64 s[100:101], 16, v239
	v_exp_f32_e32 v117, v117
	v_cndmask_b32_e32 v118, v220, v118, vcc
	v_cmp_le_i32_e32 vcc, 17, v239
	v_exp_f32_e32 v118, v118
	v_add_f32_e32 v241, v116, v117
	v_cndmask_b32_e64 v119, v220, v119, s[98:99]
	v_cmp_le_i32_e64 s[98:99], 18, v239
	v_exp_f32_e32 v119, v119
	v_add_f32_e32 v241, v241, v118
	v_mfma_f32_32x32x16_bf16 v[64:79], v[100:103], v[84:87], v[64:79]
	v_cndmask_b32_e64 v120, v220, v120, s[100:101]
	v_cmp_le_i32_e64 s[100:101], 19, v239
	v_exp_f32_e32 v120, v120
	v_add_f32_e32 v241, v241, v119
	v_cndmask_b32_e32 v121, v220, v121, vcc
	v_cmp_le_i32_e32 vcc, 24, v239
	v_exp_f32_e32 v121, v121
	v_cndmask_b32_e64 v122, v220, v122, s[98:99]
	v_cmp_le_i32_e64 s[98:99], 25, v239
	v_exp_f32_e32 v122, v122
	v_add_f32_e32 v242, v120, v121
	v_cndmask_b32_e64 v123, v220, v123, s[100:101]
	v_cmp_le_i32_e64 s[100:101], 26, v239
	v_exp_f32_e32 v123, v123
	v_add_f32_e32 v242, v242, v122
	v_cndmask_b32_e32 v124, v220, v124, vcc
	v_mfma_f32_32x32x16_bf16 v[32:47], v[108:111], v[84:87], v[32:47]
	v_cmp_le_i32_e32 vcc, 27, v239
	v_exp_f32_e32 v124, v124
	v_add_f32_e32 v242, v242, v123
	v_cndmask_b32_e64 v125, v220, v125, s[98:99]
	v_exp_f32_e32 v125, v125
	v_cndmask_b32_e64 v126, v220, v126, s[100:101]
	v_exp_f32_e32 v126, v126
	v_add_f32_e32 v243, v124, v125
	v_cndmask_b32_e32 v127, v220, v127, vcc
	v_exp_f32_e32 v127, v127
	v_add_f32_e32 v243, v243, v126
	v_add_f32_e32 v240, v240, v241
	v_add_f32_e32 v243, v243, v127
	v_add_f32_e32 v242, v242, v243
	v_add_f32_e32 v240, v240, v242
	v_add_f32_e32 v227, v227, v240
	v_cvt_pk_bf16_f32 v112, v112, v113
	v_cvt_pk_bf16_f32 v113, v114, v115
	v_cvt_pk_bf16_f32 v114, v116, v117
	v_cvt_pk_bf16_f32 v115, v118, v119
	v_cvt_pk_bf16_f32 v116, v120, v121
	v_cvt_pk_bf16_f32 v117, v122, v123
	v_cvt_pk_bf16_f32 v118, v124, v125
	v_cvt_pk_bf16_f32 v119, v126, v127
	v_mfma_f32_32x32x16_bf16 v[16:31], v[96:99], v[112:115], v[16:31]
	v_mfma_f32_32x32x16_bf16 v[0:15], v[104:107], v[112:115], v[0:15]
	v_mfma_f32_32x32x16_bf16 v[16:31], v[100:103], v[116:119], v[16:31]
	v_mfma_f32_32x32x16_bf16 v[0:15], v[108:111], v[116:119], v[0:15]
	v_add_u32_e32 v205, 0x800, v205
	s_cmp_lg_u32 s8, s66
	s_cbranch_scc1 .Lfx_loop_c4
	s_branch .Lfx_exit
.Lfx_exit:
	s_nop 7
	s_branch .LBB0_406

	.amdhsa_kernel _Z10fwd_kernel4Args
		.amdhsa_group_segment_fixed_size 0
		.amdhsa_private_segment_fixed_size 0
		.amdhsa_kernarg_size 472
		.amdhsa_user_sgpr_count 2
		.amdhsa_user_sgpr_dispatch_ptr 0
		.amdhsa_user_sgpr_queue_ptr 0
		.amdhsa_user_sgpr_kernarg_segment_ptr 1
		.amdhsa_user_sgpr_dispatch_id 0
		.amdhsa_user_sgpr_kernarg_preload_length 0
		.amdhsa_user_sgpr_kernarg_preload_offset 0
		.amdhsa_user_sgpr_private_segment_size 0
		.amdhsa_uses_dynamic_stack 0
		.amdhsa_enable_private_segment 0
		.amdhsa_system_sgpr_workgroup_id_x 1
		.amdhsa_system_sgpr_workgroup_id_y 0
		.amdhsa_system_sgpr_workgroup_id_z 0
		.amdhsa_system_sgpr_workgroup_info 0
		.amdhsa_system_vgpr_workitem_id 2
		.amdhsa_next_free_vgpr 255
		.amdhsa_next_free_sgpr 102
		.amdhsa_accum_offset 256
		.amdhsa_reserve_vcc 1
		.amdhsa_float_round_mode_32 0
		.amdhsa_float_round_mode_16_64 0
		.amdhsa_float_denorm_mode_32 3
		.amdhsa_float_denorm_mode_16_64 3
		.amdhsa_dx10_clamp 1
		.amdhsa_ieee_mode 1
		.amdhsa_fp16_overflow 0
		.amdhsa_tg_split 0
		.amdhsa_exception_fp_ieee_invalid_op 0
		.amdhsa_exception_fp_denorm_src 0
		.amdhsa_exception_fp_ieee_div_zero 0
		.amdhsa_exception_fp_ieee_overflow 0
		.amdhsa_exception_fp_ieee_underflow 0
		.amdhsa_exception_fp_ieee_inexact 0
		.amdhsa_exception_int_div_zero 0
	.end_amdhsa_kernel

amdhsa.kernels:
  - .agpr_count:     0
    .args:
      - .offset:         0
        .size:           216
        .value_kind:     by_value
      - .offset:         216
        .size:           4
        .value_kind:     hidden_block_count_x
      - .offset:         220
        .size:           4
        .value_kind:     hidden_block_count_y
      - .offset:         224
        .size:           4
        .value_kind:     hidden_block_count_z
      - .offset:         228
        .size:           2
        .value_kind:     hidden_group_size_x
      - .offset:         230
        .size:           2
        .value_kind:     hidden_group_size_y
      - .offset:         232
        .size:           2
        .value_kind:     hidden_group_size_z
      - .offset:         234
        .size:           2
        .value_kind:     hidden_remainder_x
      - .offset:         236
        .size:           2
        .value_kind:     hidden_remainder_y
      - .offset:         238
        .size:           2
        .value_kind:     hidden_remainder_z
      - .offset:         256
        .size:           8
        .value_kind:     hidden_global_offset_x
      - .offset:         264
        .size:           8
        .value_kind:     hidden_global_offset_y
      - .offset:         272
        .size:           8
        .value_kind:     hidden_global_offset_z
      - .offset:         280
        .size:           2
        .value_kind:     hidden_grid_dims
      - .offset:         304
        .size:           8
        .value_kind:     hidden_multigrid_sync_arg
      - .offset:         336
        .size:           4
        .value_kind:     hidden_dynamic_lds_size
    .group_segment_fixed_size: 0
    .kernarg_segment_align: 8
    .kernarg_segment_size: 472
    .language:       OpenCL C
    .language_version:
      - 2
      - 0
    .max_flat_workgroup_size: 512
    .name:           _Z10fwd_kernel4Args
    .private_segment_fixed_size: 0
    .sgpr_count:     108
    .sgpr_spill_count: 15
    .symbol:         _Z10fwd_kernel4Args.kd
    .uniform_work_group_size: 1
    .uses_dynamic_stack: false
    .vgpr_count:     255
    .vgpr_spill_count: 0
    .wavefront_size: 64
